# phase 3 item list: items after the first claimed from a shared counter (claim issued one item ahead)
# baseline (speedup 1.0000x reference)
.LBB0_644:
	s_mov_b32 s72, s85
	s_mov_b64 s[50:51], s[86:87]
	v_writelane_b32 v245, s88, 2
	s_or_b64 exec, exec, s[4:5]
	s_cmpk_gt_u32 s26, 0x61f
	s_cbranch_scc1 .LBB0_720
	s_waitcnt lgkmcnt(0)
	s_add_u32 s30, s14, 0x2030000
	s_addc_u32 s31, s15, 0
	s_add_u32 s3, s14, 0x1c30000
	s_addc_u32 s10, s15, 0
	s_add_u32 s11, s14, 0x1e30000
	s_addc_u32 s27, s15, 0
	s_add_u32 s36, s14, 0x1612800
	s_addc_u32 s37, s15, 0
	s_add_u32 s38, s12, 0x8e24000
	s_addc_u32 s39, s13, 0
	s_add_u32 s44, s12, 0x6e24000
	s_addc_u32 s45, s13, 0
	s_add_u32 s46, s12, 0x4e24000
	s_addc_u32 s47, s13, 0
	s_lshl_b32 s4, s26, 7
	s_add_i32 s33, s4, 0xfffdf000
	s_lshl_b32 s4, s26, 3
	s_add_i32 s43, s4, 0xffffdf00
	s_lshl_b32 s4, s26, 6
	v_mbcnt_lo_u32_b32 v0, -1, 0
	s_add_i32 s64, s4, 0xffff7800
	s_lshl_b32 s4, s26, 1
	v_mbcnt_hi_u32_b32 v71, -1, v0
	s_lshl_b32 s42, s34, 7
	s_lshl_b32 s53, s34, 3
	s_lshl_b32 s65, s34, 6
	s_add_i32 s66, s4, 0xfffffdc0
	s_lshl_b32 s4, s34, 1
	v_and_b32_e32 v0, 64, v71
	s_addk_i32 s42, 0xf000
	s_addk_i32 s53, 0xff00
	s_add_i32 s55, s26, 0xfffffbe0
	s_addk_i32 s65, 0xf800
	s_sub_i32 s67, s4, 64
	s_mov_b32 s49, 0
	v_mov_b32_e32 v65, 0
	s_add_i32 s68, 0, 0x11000
	s_movk_i32 s69, 0x210
	s_movk_i32 s70, 0x110
	s_movk_i32 s71, 0x3c00
	s_movk_i32 s73, 0x7fff
	s_mov_b32 s74, 0xffff0000
	s_movk_i32 s75, 0x4000
	s_movk_i32 s76, 0x2000
	s_movk_i32 s77, 0x1800
	s_movk_i32 s78, 0x1000
	s_movk_i32 s79, 0x3000
	s_movk_i32 s80, 0x5000
	s_mov_b32 s52, 0x358637bd
	s_mov_b32 s81, 0x800000
	s_mov_b32 s82, 0x41a00000
	s_mov_b32 s83, 0x3f2aaaab
	v_mov_b32_e32 v70, 0x3ecc95a3
	s_mov_b32 s84, 0x3f317218
	s_mov_b32 s85, 0x7f800000
	s_mov_b32 s86, 0x33800000
	s_movk_i32 s87, 0x6000
	s_movk_i32 s88, 0x7000
	s_brev_b32 s54, 60
	s_mov_b64 s[56:57], 0xf007800
	s_mov_b64 s[58:59], 0xf00b400
	v_xor_b32_e32 v72, 16, v71
	v_add_u32_e32 v73, 64, v0
	v_xor_b32_e32 v74, 32, v71
	v_mov_b32_e32 v75, 1
	v_mov_b32_e32 v66, 0x3f317218
	v_mov_b32_e32 v76, 0x7f800000
	v_mov_b32_e32 v77, 0x7fc00000
	v_mov_b32_e32 v78, 0xff800000
	v_readfirstlane_b32 s98, v156
	s_cmp_lt_u32 s98, 64
	s_cbranch_scc0 .Lq_init
	s_add_u32 s98, s40, 0x13fb3a00
	s_addc_u32 s99, s41, 0
	s_mov_b64 s[100:101], exec
	s_mov_b64 exec, 1
	v_mov_b32_e32 v246, 0
	v_mov_b32_e32 v247, 1
	global_atomic_add v246, v246, v247, s[98:99] sc0
	s_mov_b64 exec, s[100:101]
.Lq_init:
	s_branch .LBB0_648

.LBB0_647:
	v_readfirstlane_b32 s98, v156
	s_cmp_lt_u32 s98, 64
	s_cbranch_scc0 .Lq_nw0
	s_waitcnt vmcnt(0)
	v_readlane_b32 s99, v246, 0
	s_add_i32 s99, s99, 0xe0
	v_mov_b32_e32 v246, s99
	v_mov_b32_e32 v247, 0x23ff8
	ds_write_b32 v247, v246
	s_cmpk_lt_u32 s99, 0x600
	s_cbranch_scc0 .Lq_noat
	s_add_u32 s98, s40, 0x13fb3a00
	s_addc_u32 s99, s41, 0
	s_mov_b64 s[100:101], exec
	s_mov_b64 exec, 1
	v_mov_b32_e32 v246, 0
	v_mov_b32_e32 v247, 1
	global_atomic_add v246, v246, v247, s[98:99] sc0
	s_mov_b64 exec, s[100:101]

.Lq_nw0:
	s_barrier
	v_mov_b32_e32 v247, 0x23ff8
	ds_read_b32 v247, v247
	s_waitcnt lgkmcnt(0)
	v_readfirstlane_b32 s4, v247
	s_cmpk_lt_u32 s4, 0x600
	s_cbranch_scc0 .LBB0_720
	s_add_i32 s55, s4, 0xfffffc00
	s_lshl_b32 s33, s55, 7
	s_lshl_b32 s43, s55, 3
	s_add_i32 s64, s4, 0xfffffe00
	s_lshl_b32 s64, s64, 6
	s_add_i32 s66, s4, 0xffffff00
	s_lshl_b32 s66, s66, 1

	.amdhsa_kernel _Z10fwd_kernel4Args
		.amdhsa_group_segment_fixed_size 0
		.amdhsa_private_segment_fixed_size 0
		.amdhsa_kernarg_size 496
		.amdhsa_user_sgpr_count 2
		.amdhsa_user_sgpr_dispatch_ptr 0
		.amdhsa_user_sgpr_queue_ptr 0
		.amdhsa_user_sgpr_kernarg_segment_ptr 1
		.amdhsa_user_sgpr_dispatch_id 0
		.amdhsa_user_sgpr_kernarg_preload_length 0
		.amdhsa_user_sgpr_kernarg_preload_offset 0
		.amdhsa_user_sgpr_private_segment_size 0
		.amdhsa_uses_dynamic_stack 0
		.amdhsa_enable_private_segment 0
		.amdhsa_system_sgpr_workgroup_id_x 1
		.amdhsa_system_sgpr_workgroup_id_y 0
		.amdhsa_system_sgpr_workgroup_id_z 0
		.amdhsa_system_sgpr_workgroup_info 0
		.amdhsa_system_vgpr_workitem_id 2
		.amdhsa_next_free_vgpr 248
		.amdhsa_next_free_sgpr 102
		.amdhsa_accum_offset 248
		.amdhsa_reserve_vcc 1
		.amdhsa_float_round_mode_32 0
		.amdhsa_float_round_mode_16_64 0
		.amdhsa_float_denorm_mode_32 3
		.amdhsa_float_denorm_mode_16_64 3
		.amdhsa_dx10_clamp 1
		.amdhsa_ieee_mode 1
		.amdhsa_fp16_overflow 0
		.amdhsa_tg_split 0
		.amdhsa_exception_fp_ieee_invalid_op 0
		.amdhsa_exception_fp_denorm_src 0
		.amdhsa_exception_fp_ieee_div_zero 0
		.amdhsa_exception_fp_ieee_overflow 0
		.amdhsa_exception_fp_ieee_underflow 0
		.amdhsa_exception_fp_ieee_inexact 0
		.amdhsa_exception_int_div_zero 0
	.end_amdhsa_kernel

amdhsa.kernels:
  - .agpr_count:     0
    .args:
      - .offset:         0
        .size:           240
        .value_kind:     by_value
      - .offset:         240
        .size:           4
        .value_kind:     hidden_block_count_x
      - .offset:         244
        .size:           4
        .value_kind:     hidden_block_count_y
      - .offset:         248
        .size:           4
        .value_kind:     hidden_block_count_z
      - .offset:         252
        .size:           2
        .value_kind:     hidden_group_size_x
      - .offset:         254
        .size:           2
        .value_kind:     hidden_group_size_y
      - .offset:         256
        .size:           2
        .value_kind:     hidden_group_size_z
      - .offset:         258
        .size:           2
        .value_kind:     hidden_remainder_x
      - .offset:         260
        .size:           2
        .value_kind:     hidden_remainder_y
      - .offset:         262
        .size:           2
        .value_kind:     hidden_remainder_z
      - .offset:         280
        .size:           8
        .value_kind:     hidden_global_offset_x
      - .offset:         288
        .size:           8
        .value_kind:     hidden_global_offset_y
      - .offset:         296
        .size:           8
        .value_kind:     hidden_global_offset_z
      - .offset:         304
        .size:           2
        .value_kind:     hidden_grid_dims
      - .offset:         328
        .size:           8
        .value_kind:     hidden_multigrid_sync_arg
      - .offset:         360
        .size:           4
        .value_kind:     hidden_dynamic_lds_size
    .group_segment_fixed_size: 0
    .kernarg_segment_align: 8
    .kernarg_segment_size: 496
    .language:       OpenCL C
    .language_version:
      - 2
      - 0
    .max_flat_workgroup_size: 512
    .name:           _Z10fwd_kernel4Args
    .private_segment_fixed_size: 0
    .sgpr_count:     108
    .sgpr_spill_count: 621
    .symbol:         _Z10fwd_kernel4Args.kd
    .uniform_work_group_size: 1
    .uses_dynamic_stack: false
    .vgpr_count:     248
    .vgpr_spill_count: 0
    .wavefront_size: 64
